# LRU pass A: redundant barrier at the top of each item removed (all readers of the us/ucb region are behind the previous item's last barrier)
# baseline (speedup 1.0000x reference)
; template <bool PASS_C>
; DEVI void lru_item(const P& p, int item, int next_item, uint4& u0, uint4& u1, uint4& u2, float& cpre, char* smem) {
;     ...
;     __syncthreads();
;     *(uint4*)(us + tid * 8) = u0;
;     *(uint4*)(us + (tid + 256) * 8) = u1;
;     if (tid < 24) *(uint4*)(us + (tid + 512) * 8) = u2;
;     if (PASS_C && tid < 128) carry[tid] = cpre;
;     uint4 sg0 = {0u, 0u, 0u, 0u}, sg1 = {0u, 0u, 0u, 0u};
;     if (PASS_C) {
;         const bf16_t* SG = (const bf16_t*)(p.ws + OFF_C) + (rbase + tb + (tid >> 2)) * 1024 + h * 64 + (tid & 3) * 16;
;         sg0 = *(const uint4*)(SG); sg1 = *(const uint4*)(SG + 8);
;     }
;     if (next_item >= 0) {
;         lru_load_us(p, next_item, tid, u0, u1, u2);
;         if (PASS_C && tid < 128) {
;             const int nh = next_item & 15, nc = (next_item >> 4) % NCH, nb = next_item / (16 * NCH);
;             cpre = ((const float*)(p.ws + OFF_CIN))[(size_t)(nb * NCH + nc) * 2048 + (tid >> 6) * 1024 + nh * 64 + (tid & 63)];
;         }
;     }
.LBB0_500:
	s_waitcnt vmcnt(1) lgkmcnt(0)
	ds_write_b128 v140, v[4:7] offset:35840
	ds_write_b128 v140, v[0:3] offset:39936
	s_and_saveexec_b64 s[12:13], s[6:7]
	ds_write_b128 v140, v[8:11] offset:44032
	s_or_b64 exec, exec, s[12:13]
	s_add_i32 s36, s34, s27
	s_cmpk_gt_i32 s36, 0x21ff
	s_cselect_b64 s[14:15], -1, 0
	s_cmpk_lt_i32 s36, 0x2200
	s_cselect_b32 s12, s36, -1
	s_cmp_lt_i32 s12, 0
	s_cbranch_scc1 .LBB0_510
	s_lshr_b32 s0, s12, 4
	s_mul_hi_u32 s13, s0, 0x3c3c3c4
	s_mulk_i32 s13, 0x44
	s_sub_i32 s17, s0, s13
	s_mul_hi_u32 s0, s12, 0xf0f0f0f1
	s_lshr_b32 s13, s0, 10
	s_cmp_lt_u32 s17, 4
	s_mul_hi_u32 s18, s13, 0x880000
	s_mul_i32 s13, s13, 0x880000
	s_cselect_b32 s0, 0, 0x100
	s_cselect_b32 s16, 0x100, s31
	s_add_u32 s13, s80, s13
	s_addc_u32 s18, s81, s18
	s_lshl_b32 s12, s12, 7
	s_and_b32 s12, s12, 0x780
	s_add_u32 s12, s13, s12
	s_addc_u32 s13, s18, 0
	v_mov_b32_e32 v89, v69
	v_lshl_add_u32 v8, s17, 6, v110
	v_mov_b32_e32 v2, v69
	v_mov_b32_e32 v3, v69
	v_lshl_add_u64 v[12:13], s[12:13], 0, v[88:89]
	v_cmp_le_i32_e32 vcc, s0, v8
	v_cmp_gt_i32_e64 s[12:13], s16, v8
	v_mov_b32_e32 v0, 0
	v_mov_b32_e32 v1, v69
	v_mov_b64_e32 v[6:7], v[2:3]
	s_and_b64 s[18:19], vcc, s[12:13]
	v_mov_b64_e32 v[4:5], v[0:1]
	s_and_saveexec_b64 s[12:13], s[18:19]
	s_cbranch_execz .LBB0_505
	v_mov_b32_e32 v9, v69
	v_lshlrev_b64 v[4:5], 11, v[8:9]
	v_lshl_add_u64 v[4:5], v[12:13], 0, v[4:5]
	global_load_dwordx4 v[4:7], v[4:5], off
